# attention K/V staging (ds_write + next loads) batched at the top of each sub-iteration; heads of the hand-written loops placed on 64-byte boundaries
# baseline (speedup 1.0000x reference)
; DI void gemm256(const char* a_u, unsigned a_voff, size_t astep, const char* b_u, unsigned b_voff, size_t bstep, int nk, char* smem, f32x16 (&acc)[4][2]) {
;     ...
;   for (int kt = 0; kt < nk; ++kt) {
;     const int cur = kt & 1, k2 = (kt + 2 < last) ? kt + 2 : last;
;     const char* S = smem + cur * 2 * T2;
;     char* D = smem + (cur ^ 1) * 2 * T2;
;     const char* an = a_u + (size_t)k2 * 128;
;     const char* bn = b_u + (size_t)k2 * 128;
; #pragma unroll
;     for (int s = 0; s < 4; ++s) {
;       bf16x8 a[4], b[2];
; #pragma unroll
;       for (int mi = 0; mi < 4; ++mi) a[mi] = *(const bf16x8*)(S + aoff + mi * 32 * LROW + s * 32);
; #pragma unroll
;       for (int ni = 0; ni < 2; ++ni) b[ni] = *(const bf16x8*)(S + boff + ni * 32 * LROW + s * 32);
.Lg_inproj_go:
	ds_read_b128 v[196:199], v194 offset:0
	ds_read_b128 v[212:215], v160 offset:0
	ds_read_b128 v[216:219], v160 offset:2048
	ds_read_b128 v[242:245], v160 offset:4096
	ds_read_b128 v[246:249], v160 offset:6144
	ds_read_b128 v[200:203], v194 offset:4096
	ds_read_b128 v[204:207], v194 offset:8192
	ds_read_b128 v[208:211], v194 offset:12288
	.p2alignl 6, 3212836864

; DI int tid512() { int t = threadIdx.x; asm volatile("" : "+v"(t)); return t; }
; #define A_LOAD(KB) { _Pragma("unroll") for (int i = 0; i < 2; ++i) { rk[i] = *(const u32x4*)(kp + (size_t)((KB) * 64 + 32 * i) * 1024); rv[i] = *(const u32x4*)(vp + (size_t)(64 * i) * TOK + (KB) * 64); } }
; #define A_STORE(STG) { char* D_ = smem + (STG) * ST; _Pragma("unroll") for (int i = 0; i < 2; ++i) { *(u32x4*)(D_ + ksoff + i * 32 * 272) = rk[i]; \
;       u32x2 lo2_ = {rv[i].x, rv[i].y}, hi2_ = {rv[i].z, rv[i].w}; *(u32x2*)(D_ + vsoff + i * 64 * VROW) = lo2_; *(u32x2*)(D_ + vsoff + i * 64 * VROW + 16) = hi2_; } }
; DI void attn_block(const Params& p, int layer, int hd, int q0, int nkeys, char* smem) {
;     ...
;   const int t = tid512(), lane = t & 63, w = t >> 6, mp = w >> 2, wq = w & 3, r = lane & 31, h = lane >> 5;
;   const bf16_t* DQ = (const bf16_t*)(p.ws + O_DQ);
;   const bf16_t* DK = (const bf16_t*)(p.ws + O_DK);
;   const bf16_t* DVT = (const bf16_t*)(p.ws + O_DVT);
;   const float* scal = (const float*)(p.ws + O_SCAL);
;   const int q = q0 + 32 * wq + r;
;   bf16x8 qf[4];
; #pragma unroll
;   for (int s = 0; s < 4; ++s) qf[s] = *(const bf16x8*)(DQ + (size_t)q * 1024 + hd * 128 + 64 * mp + 16 * s + 8 * h);
;   const int nkb = nkeys >> 6, lastkb = nkb - 1;
;   const bf16_t* kp = DK + (size_t)(t >> 4) * 1024 + hd * 128 + (t & 15) * 8;
;   const int ksoff = (t >> 4) * 272 + (t & 15) * 16;
;   const bf16_t* vp = DVT + (size_t)(hd * 128 + (t >> 3)) * TOK + (t & 7) * 8;
;   const int vsoff = KT + (t >> 3) * VROW + ((t & 7) >> 1) * 32 + (t & 1) * 8;
;   u32x4 rk[2], rv[2];
;     ...
;   A_LOAD(0);
;   __syncthreads();
;   A_STORE(0);
;   A_LOAD(lastkb < 1 ? lastkb : 1);
;   A_STORE(1);
;   A_LOAD(lastkb < 2 ? lastkb : 2);
;   __syncthreads();
.LBB0_392:
	s_lshl_b32 s4, s6, 7
	v_mov_b32_e32 v202, v0
	s_and_b32 s4, s4, 0x1f80
	s_addk_i32 s4, 0x100
	v_lshrrev_b32_e32 v2, 1, v202
	v_and_b32_e32 v200, 31, v202
	v_and_b32_e32 v201, 0x60, v2
	v_or3_b32 v198, v200, s4, v201
	v_readlane_b32 s4, v254, 9
	v_lshlrev_b32_e32 v180, 11, v198
	v_readlane_b32 s5, v254, 10
	v_ashrrev_i32_e32 v199, 8, v202
	v_lshlrev_b32_e32 v4, 6, v199
	v_lshl_add_u64 v[2:3], s[4:5], 0, v[180:181]
	s_lshl_b32 s4, s6, 1
	s_and_b32 s94, s4, 0x7fffff80
	s_lshl_b32 s22, s94, 1
	v_bfe_u32 v193, v202, 5, 1
	v_lshl_add_u64 v[2:3], v[2:3], 0, s[22:23]
	v_ashrrev_i32_e32 v5, 31, v4
	v_lshl_add_u64 v[2:3], v[4:5], 1, v[2:3]
	v_lshlrev_b32_e32 v180, 4, v193
	v_ashrrev_i32_e32 v34, 4, v202
	v_lshl_add_u64 v[2:3], v[2:3], 0, v[180:181]
	v_ashrrev_i32_e32 v35, 31, v34
	v_readlane_b32 s4, v254, 11
	global_load_dwordx4 v[130:133], v[2:3], off
	global_load_dwordx4 v[134:137], v[2:3], off offset:32
	global_load_dwordx4 v[138:141], v[2:3], off offset:64
	global_load_dwordx4 v[142:145], v[2:3], off offset:96
	v_lshlrev_b64 v[2:3], 11, v[34:35]
	v_readlane_b32 s5, v254, 12
	v_lshlrev_b32_e32 v35, 4, v202
	v_and_b32_e32 v36, 0xf0, v35
	v_lshl_add_u64 v[2:3], s[4:5], 0, v[2:3]
	v_lshl_add_u64 v[2:3], v[2:3], 0, s[22:23]
	v_mov_b32_e32 v37, v181
	v_readlane_b32 s4, v253, 54
	v_lshl_add_u64 v[162:163], v[2:3], 0, v[36:37]
	v_ashrrev_i32_e32 v37, 3, v202
	v_readlane_b32 s5, v253, 55
	v_add_u32_e32 v4, s94, v37
	v_mov_b32_e32 v5, v181
	v_mov_b64_e32 v[2:3], s[4:5]
	v_mad_i64_i32 v[2:3], s[4:5], v4, s29, v[2:3]
	v_and_b32_e32 v4, 7, v202
	v_lshlrev_b32_e32 v4, 4, v4
	v_add_co_u32_e32 v10, vcc, s46, v162
	v_lshl_add_u64 v[164:165], v[2:3], 0, v[4:5]
	s_nop 0
	v_addc_co_u32_e32 v11, vcc, 0, v163, vcc
	v_add_co_u32_e32 v38, vcc, s30, v164
	global_load_dwordx4 v[2:5], v[162:163], off
	global_load_dwordx4 v[6:9], v[164:165], off
	v_addc_co_u32_e32 v39, vcc, 0, v165, vcc
	v_add_co_u32_e32 v18, vcc, s87, v162
	global_load_dwordx4 v[10:13], v[10:11], off
	s_nop 0
	global_load_dwordx4 v[14:17], v[38:39], off
	v_addc_co_u32_e32 v19, vcc, 0, v163, vcc
	v_add_co_u32_e32 v26, vcc, s47, v162
	s_waitcnt vmcnt(63) expcnt(7) lgkmcnt(15)
	s_barrier
	global_load_dwordx4 v[18:21], v[18:19], off
	s_nop 0
	global_load_dwordx4 v[22:25], v[164:165], off offset:128
	v_addc_co_u32_e32 v27, vcc, 0, v163, vcc
	global_load_dwordx4 v[26:29], v[26:27], off
	s_nop 0
	global_load_dwordx4 v[30:33], v[38:39], off offset:128
	v_lshlrev_b32_e32 v40, 3, v202
	v_mul_lo_u32 v37, v37, s28
	s_movk_i32 s4, 0x110
	v_and_b32_e32 v35, 0x60, v35
	v_mad_u64_u32 v[194:195], s[4:5], v34, s4, v[36:37]
	v_and_or_b32 v34, v40, 8, v37
	v_add_u32_e32 v205, v34, v35
	v_add_u32_e32 v36, 16, v194
	v_add_u32_e32 v34, 16, v205
	v_add_u32_e32 v35, 0x4000, v34
	v_add_u32_e32 v37, 0x6800, v34
	v_add_u32_e32 v40, 0xd000, v34
	global_load_dwordx4 v[146:149], v[164:165], off offset:256
	s_mov_b32 s4, 0x50000
	s_mov_b32 s42, 1
	v_mul_u32_u24_e32 v203, 0x90, v200
	v_mov_b32_e32 v204, 0xf149f2ca
	v_mov_b32_e32 v195, 0
	s_waitcnt vmcnt(0)
	ds_write_b128 v36, v[2:5]
	ds_write2_b64 v35, v[6:7], v[8:9] offset0:128 offset1:130
	ds_write_b128 v36, v[10:13] offset:8704
	ds_write2_b64 v37, v[14:15], v[16:17] offset1:2
	ds_write_b128 v36, v[18:21] offset:35840
	ds_write2_b64 v40, v[22:23], v[24:25] offset1:2
	ds_write_b128 v36, v[26:29] offset:44544
	v_add_u32_e32 v2, 0xf000, v34
	ds_write2_b64 v2, v[30:31], v[32:33] offset0:128 offset1:130
	v_add_co_u32_e32 v2, vcc, s84, v162
	global_load_dwordx4 v[150:153], v[38:39], off offset:256
	s_nop 0
	v_addc_co_u32_e32 v3, vcc, 0, v163, vcc
	v_add_co_u32_e32 v4, vcc, s4, v162
	s_mov_b32 s4, 0
	s_nop 0
	v_addc_co_u32_e32 v5, vcc, 0, v163, vcc
	global_load_dwordx4 v[158:161], v[2:3], off
	global_load_dwordx4 v[154:157], v[4:5], off
	v_lshl_add_u32 v2, v199, 7, 16
	v_mul_u32_u24_e32 v3, 0x110, v200
	v_add3_u32 v206, v2, v180, v3
	s_waitcnt lgkmcnt(0)
	s_barrier
; #define A_LOAD(KB) { _Pragma("unroll") for (int i = 0; i < 2; ++i) { rk[i] = *(const u32x4*)(kp + (size_t)((KB) * 64 + 32 * i) * 1024); rv[i] = *(const u32x4*)(vp + (size_t)(64 * i) * TOK + (KB) * 64); } }
; #define A_STORE(STG) { char* D_ = smem + (STG) * ST; _Pragma("unroll") for (int i = 0; i < 2; ++i) { *(u32x4*)(D_ + ksoff + i * 32 * 272) = rk[i]; \
;       u32x2 lo2_ = {rv[i].x, rv[i].y}, hi2_ = {rv[i].z, rv[i].w}; *(u32x2*)(D_ + vsoff + i * 64 * VROW) = lo2_; *(u32x2*)(D_ + vsoff + i * 64 * VROW + 16) = hi2_; } }
; #define A_SCORES(DST, STG) { const char* Ks_ = smem + (STG) * ST; _Pragma("unroll") for (int kt = 0; kt < 2; ++kt) { \
;       _Pragma("unroll") for (int i = 0; i < 16; ++i) DST[kt][i] = 0.f; \
;       _Pragma("unroll") for (int s = 0; s < 4; ++s) { const bf16x8 a_ = *(const bf16x8*)(Ks_ + (32 * kt + r) * 272 + 128 * mp + 32 * s + 16 * h); DST[kt] = MFMA32(a_, qf[s], DST[kt]); } } }
; DI void attn_block(const Params& p, int layer, int hd, int q0, int nkeys, char* smem) {
;     ...
;   float m = -1e30f, l = 0.f;
;   f32x16 o[4];
; #pragma unroll
;   for (int vt = 0; vt < 4; ++vt)
; #pragma unroll
;     for (int i = 0; i < 16; ++i) o[vt][i] = 0.f;
;   f32x16 sc[2], sn[2];
;   A_SCORES(sc, 0);
;   int c0 = 0, c1 = 1, c2 = 2;
;   for (int kb = 0; kb < nkb; ++kb) {
;     const char* Vs = smem + c0 * ST + KT;
;     A_STORE(c2);
;     A_LOAD((kb + 3 < lastkb) ? kb + 3 : lastkb);
;     if (kb + 1 < nkb) A_SCORES(sn, c1);
;     float mx = fmaxf(sc[0][0], sc[1][0]);
; #pragma unroll
;     for (int i = 1; i < 16; ++i) mx = fmaxf(mx, fmaxf(sc[0][i], sc[1][i]));
;     {
;       const auto pr_ = __builtin_amdgcn_permlane32_swap(__float_as_uint(mx), __float_as_uint(mx), false, false);
;       mx = fmaxf(__uint_as_float(pr_[0]), __uint_as_float(pr_[1]));
;     }
	ds_read_b128 v[2:5], v206
	ds_read_b128 v[6:9], v206 offset:32
	s_waitcnt lgkmcnt(1)
	v_mfma_f32_32x32x16_bf16 v[114:129], v[2:5], v[130:133], 0
	s_mov_b32 s18, s4
	s_mov_b32 s19, s4
	s_mov_b32 s5, s4
	s_mov_b32 s6, s4
	s_mov_b32 s7, s4
	s_mov_b32 s8, s4
	s_mov_b32 s9, s4
	s_waitcnt lgkmcnt(0)
	v_mfma_f32_32x32x16_bf16 v[114:129], v[6:9], v[134:137], v[114:129]
	ds_read_b128 v[2:5], v206 offset:64
	ds_read_b128 v[6:9], v206 offset:96
	s_mov_b32 s10, s4
	s_mov_b32 s11, s4
	s_mov_b32 s12, s4
	s_mov_b32 s13, s4
	s_mov_b32 s14, s4
	s_mov_b32 s15, s4
	s_waitcnt lgkmcnt(1)
	v_mfma_f32_32x32x16_bf16 v[114:129], v[2:5], v[138:141], v[114:129]
	ds_read_b128 v[2:5], v206 offset:8704
	ds_read_b128 v[10:13], v206 offset:8736
	s_mov_b32 s16, s4
	s_mov_b32 s17, s4
	v_mov_b64_e32 v[64:65], s[18:19]
	v_mov_b64_e32 v[50:51], s[4:5]
	v_mov_b64_e32 v[62:63], s[16:17]
	v_mov_b64_e32 v[60:61], s[14:15]
	s_waitcnt lgkmcnt(1)
	v_mfma_f32_32x32x16_bf16 v[98:113], v[2:5], v[130:133], 0
	ds_read_b128 v[2:5], v206 offset:8768
	v_mov_b64_e32 v[58:59], s[12:13]
	v_mov_b64_e32 v[56:57], s[10:11]
	v_mov_b64_e32 v[54:55], s[8:9]
	v_mov_b64_e32 v[52:53], s[6:7]
	v_mov_b64_e32 v[18:19], v[50:51]
	v_mov_b64_e32 v[34:35], v[50:51]
	s_waitcnt lgkmcnt(1)
	v_mfma_f32_32x32x16_bf16 v[98:113], v[10:13], v[134:137], v[98:113]
	s_mov_b32 s5, 2
	v_mov_b64_e32 v[20:21], v[52:53]
	v_mov_b64_e32 v[22:23], v[54:55]
	v_mov_b64_e32 v[24:25], v[56:57]
	v_mov_b64_e32 v[26:27], v[58:59]
	v_mov_b64_e32 v[28:29], v[60:61]
	v_mov_b64_e32 v[30:31], v[62:63]
	v_mfma_f32_32x32x16_bf16 v[114:129], v[6:9], v[142:145], v[114:129]
	ds_read_b128 v[6:9], v206 offset:8800
	v_mov_b64_e32 v[32:33], v[64:65]
	v_mov_b64_e32 v[36:37], v[52:53]
	v_mov_b64_e32 v[38:39], v[54:55]
	v_mov_b64_e32 v[40:41], v[56:57]
	v_mov_b64_e32 v[42:43], v[58:59]
	v_mov_b64_e32 v[44:45], v[60:61]
	s_waitcnt lgkmcnt(1)
	v_mfma_f32_32x32x16_bf16 v[98:113], v[2:5], v[138:141], v[98:113]
	v_mov_b64_e32 v[46:47], v[62:63]
	v_mov_b64_e32 v[48:49], v[64:65]
	s_waitcnt lgkmcnt(0)
	v_mfma_f32_32x32x16_bf16 v[98:113], v[6:9], v[142:145], v[98:113]
	v_mov_b64_e32 v[2:3], v[50:51]
	v_mov_b64_e32 v[4:5], v[52:53]
	v_mov_b64_e32 v[6:7], v[54:55]
	v_mov_b64_e32 v[8:9], v[56:57]
	v_mov_b64_e32 v[10:11], v[58:59]
	v_mov_b64_e32 v[12:13], v[60:61]
	v_mov_b64_e32 v[14:15], v[62:63]
	v_mov_b64_e32 v[16:17], v[64:65]
	v_mov_b32_e32 v196, 0x1a410
	v_lshl_add_u32 v196, v0, 2, v196
	ds_write_b32 v196, v170 offset:0
	ds_write_b32 v196, v171 offset:2048
	ds_write_b32 v196, v172 offset:4096
	ds_write_b32 v196, v173 offset:6144
	ds_write_b32 v196, v174 offset:8192
	ds_write_b32 v196, v175 offset:10240
	ds_write_b32 v196, v176 offset:12288
	ds_write_b32 v196, v177 offset:14336
	s_waitcnt lgkmcnt(0)
	ds_write_b32 v196, v178 offset:16384
	ds_write_b32 v196, v179 offset:18432
	v_readfirstlane_b32 s52, v162
	v_readfirstlane_b32 s53, v163
	v_readfirstlane_b32 s56, v164
	v_readfirstlane_b32 s57, v165
	s_nop 3
	s_add_u32 s54, s52, s46
	s_addc_u32 s55, s53, 0
	s_add_u32 s58, s56, s30
	s_addc_u32 s59, s57, 0
	v_subrev_u32_e32 v175, s52, v162
	v_subrev_u32_e32 v176, s56, v164
	v_add_u32_e32 v162, 0x11800, v206
	v_add3_u32 v163, v203, v180, 16
	v_add_u32_e32 v174, 0x11810, v205
	v_add_u32_e32 v165, 0x11810, v194
	v_add_u32_e32 v164, 0xd000, v163
	s_mov_b32 s6, 0
	s_nop 7
	v_max3_f32 v178, v114, v115, v116
	v_max3_f32 v179, v117, v118, v119
	v_max3_f32 v178, v178, v120, v121
	v_max3_f32 v179, v179, v122, v123
	v_max3_f32 v178, v178, v124, v125
	v_max3_f32 v179, v179, v126, v127
	v_max3_f32 v178, v178, v128, v129
	v_max3_f32 v179, v179, v98, v99
	v_max3_f32 v178, v178, v100, v101
	v_max3_f32 v179, v179, v102, v103
	v_max3_f32 v178, v178, v104, v105
	v_max3_f32 v179, v179, v106, v107
	v_max3_f32 v178, v178, v108, v109
	v_max3_f32 v179, v179, v110, v111
	v_max3_f32 v178, v178, v112, v113
	v_max_f32_e32 v178, v178, v179
	v_mov_b32_e32 v179, v178
	s_nop 1
	v_permlane32_swap_b32_e32 v178, v179
	v_max_f32_e32 v178, v178, v179
	v_sub_f32_e32 v114, v114, v178
	v_sub_f32_e32 v115, v115, v178
	v_sub_f32_e32 v116, v116, v178
	v_sub_f32_e32 v117, v117, v178
	v_sub_f32_e32 v118, v118, v178
	v_sub_f32_e32 v119, v119, v178
	v_sub_f32_e32 v120, v120, v178
	v_sub_f32_e32 v121, v121, v178
	v_sub_f32_e32 v122, v122, v178
	v_sub_f32_e32 v123, v123, v178
	v_sub_f32_e32 v124, v124, v178
	v_sub_f32_e32 v125, v125, v178
	v_sub_f32_e32 v126, v126, v178
	v_sub_f32_e32 v127, v127, v178
	v_sub_f32_e32 v128, v128, v178
	v_sub_f32_e32 v129, v129, v178
	v_sub_f32_e32 v98, v98, v178
	v_sub_f32_e32 v99, v99, v178
	v_sub_f32_e32 v100, v100, v178
	v_sub_f32_e32 v101, v101, v178
	v_sub_f32_e32 v102, v102, v178
	v_sub_f32_e32 v103, v103, v178
	v_sub_f32_e32 v104, v104, v178
	v_sub_f32_e32 v105, v105, v178
	v_sub_f32_e32 v106, v106, v178
	v_sub_f32_e32 v107, v107, v178
	v_sub_f32_e32 v108, v108, v178
	v_sub_f32_e32 v109, v109, v178
	v_sub_f32_e32 v110, v110, v178
	v_sub_f32_e32 v111, v111, v178
	v_sub_f32_e32 v112, v112, v178
	v_sub_f32_e32 v113, v113, v178
	v_mul_f32_e32 v66, -1.0, v178
	v_mov_b32_e32 v197, 0
	v_mov_b32_e32 v207, 0
	v_mov_b32_e32 v67, v66
	v_mov_b32_e32 v68, v66
	v_mov_b32_e32 v69, v66
	v_mov_b32_e32 v70, v66
	v_mov_b32_e32 v71, v66
	v_mov_b32_e32 v72, v66
	v_mov_b32_e32 v73, v66
	v_mov_b32_e32 v74, v66
	v_mov_b32_e32 v75, v66
	v_mov_b32_e32 v76, v66
	v_mov_b32_e32 v77, v66
	v_mov_b32_e32 v78, v66
	v_mov_b32_e32 v79, v66
	v_mov_b32_e32 v80, v66
	v_mov_b32_e32 v81, v66
	s_waitcnt vmcnt(0)
	s_waitcnt lgkmcnt(0)
	ds_read_b128 v[220:223], v163 offset:17408
	ds_read_b128 v[208:211], v206 offset:35840
	ds_read_b128 v[224:227], v163 offset:22016
	ds_read_b128 v[212:215], v206 offset:35872
	ds_read_b128 v[228:231], v163 offset:26624
	ds_read_b128 v[216:219], v206 offset:35904
	ds_read_b128 v[238:241], v163 offset:31232
	.p2alignl 6, 3212836864

; DI int tid512() { int t = threadIdx.x; asm volatile("" : "+v"(t)); return t; }
; DI unsigned voff256(size_t ld) { const int t = tid512(); return (unsigned)(((size_t)(t >> 3) * ld + (t & 7) * 8) * 2); }
; DI void gemm256(const char* a_u, unsigned a_voff, size_t astep, const char* b_u, unsigned b_voff, size_t bstep, int nk, char* smem, f32x16 (&acc)[4][2]) {
;   asm volatile("" : "+s"(nk));
;   const int t = tid512(), lane = t & 63, w = t >> 6, wm = w >> 2, wn = w & 3, r = lane & 31, h = lane >> 5;
;   const int soff = (t >> 3) * LROW + (t & 7) * 16;
;   const int aoff = (128 * wm + r) * LROW + h * 16, boff = T2 + (64 * wn + r) * LROW + h * 16;
;   u32x4 ra[4], rb[4];
; #pragma unroll
;   for (int i = 0; i < 4; ++i) { ra[i] = *(const u32x4*)(a_u + i * astep + a_voff); rb[i] = *(const u32x4*)(b_u + i * bstep + b_voff); }
;   __syncthreads();
; #pragma unroll
;   for (int i = 0; i < 4; ++i) { *(u32x4*)(smem + soff + i * 64 * LROW) = ra[i]; *(u32x4*)(smem + T2 + soff + i * 64 * LROW) = rb[i]; }
;   const int last = nk - 1;
;   {
;     const int k1 = last < 1 ? last : 1;
; #pragma unroll
;     for (int i = 0; i < 4; ++i) { ra[i] = *(const u32x4*)(a_u + i * astep + k1 * 128 + a_voff); rb[i] = *(const u32x4*)(b_u + i * bstep + k1 * 128 + b_voff); }
;   }
;   __syncthreads();
; DI void outproj256(const Params& p, int layer, char* smem) {
;     ...
;   for (int i = 0;; ++i) {
;     const int L = tile_of(i, 32 * 8);
;     if (L < 0) break;
;     int tm, tn; tile_mn(L, 32, 8, tm, tn);
;     f32x16 acc[4][2]; zero_acc256(acc);
;     gemm256((const char*)(Yb + (size_t)(256 + tm * 256) * DM), voff256(DM), (size_t)128 * DM, (const char*)(W + (size_t)(tn * 256) * DM), voff256(DM), (size_t)128 * DM, DM / 64, smem, acc);
.LBB0_918:
	s_lshr_b32 s4, s6, 3
	s_and_b32 s5, s4, 0xffffffc
	s_sub_i32 s4, 32, s5
	s_min_i32 s7, s4, 4
	s_abs_i32 s8, s7
	v_cvt_f32_u32_e32 v2, s8
	s_sub_i32 s9, 0, s8
	s_and_b32 s6, s6, 31
	s_ashr_i32 s4, s7, 31
	v_rcp_iflag_f32_e32 v2, v2
	v_mov_b32_e32 v37, v181
	v_mul_f32_e32 v2, 0x4f7ffffe, v2
	v_cvt_u32_f32_e32 v2, v2
	s_nop 0
	v_readfirstlane_b32 s13, v2
	s_mul_i32 s9, s9, s13
	s_mul_hi_u32 s9, s13, s9
	s_add_i32 s13, s13, s9
	s_mul_hi_u32 s9, s6, s13
	s_mul_i32 s13, s9, s8
	s_sub_i32 s13, s6, s13
	s_add_i32 s14, s9, 1
	s_sub_i32 s15, s13, s8
	s_cmp_ge_u32 s13, s8
	s_cselect_b32 s9, s14, s9
	s_cselect_b32 s13, s15, s13
	s_add_i32 s14, s9, 1
	s_cmp_ge_u32 s13, s8
	s_cselect_b32 s8, s14, s9
	s_xor_b32 s8, s8, s4
	s_sub_i32 s4, s8, s4
	s_mul_i32 s7, s4, s7
	s_sub_i32 s6, s6, s7
	s_add_i32 s6, s6, s5
	s_lshl_b32 s5, s6, 8
	s_add_i32 s22, s5, 0x100
	s_lshl_b64 s[6:7], s[22:23], 12
	v_readlane_b32 s5, v254, 20
	v_mov_b32_e32 v2, v0
	s_add_u32 s6, s5, s6
	v_readlane_b32 s5, v254, 21
	s_addc_u32 s7, s5, s7
	v_lshlrev_b32_e32 v3, 4, v2
	v_and_b32_e32 v3, 0x70, v3
	v_lshlrev_b32_e32 v2, 9, v2
	s_movk_i32 s13, 0xf000
	s_lshl_b32 s4, s4, 8
	v_and_or_b32 v180, v2, s13, v3
	s_ashr_i32 s5, s4, 31
	v_mov_b32_e32 v2, v0
	s_lshl_b64 s[8:9], s[4:5], 12
	s_add_u32 s8, s10, s8
	v_lshlrev_b32_e32 v3, 4, v2
	v_and_b32_e32 v3, 0x70, v3
	v_lshlrev_b32_e32 v2, 9, v2
	v_lshl_add_u64 v[162:163], s[6:7], 0, v[180:181]
	s_addc_u32 s9, s11, s9
	v_and_or_b32 v36, v2, s13, v3
	v_add_co_u32_e32 v12, vcc, s84, v162
	v_lshl_add_u64 v[164:165], s[8:9], 0, v[36:37]
	s_nop 0
	v_addc_co_u32_e32 v13, vcc, 0, v163, vcc
	v_add_co_u32_e32 v16, vcc, s84, v164
	s_mov_b32 s5, 32
	v_mov_b32_e32 v2, v0
	v_addc_co_u32_e32 v17, vcc, 0, v165, vcc
	v_add_co_u32_e32 v20, vcc, s31, v162
	v_lshlrev_b32_e32 v4, 4, v2
	v_and_b32_e32 v38, 0x70, v4
	v_lshrrev_b32_e32 v132, 6, v0
	s_nop 0
	v_readfirstlane_b32 s61, v132
	v_and_b32_e32 v132, 63, v0
	v_and_b32_e32 v133, 15, v132
	v_lshrrev_b32_e32 v136, 4, v132
	v_bfe_u32 v137, v133, 1, 3
	v_lshlrev_b32_e32 v133, 7, v133
	s_lshr_b32 s60, s61, 2
	s_lshl_b32 s60, s60, 14
	s_add_i32 s60, s60, 16
	s_and_b32 s62, s61, 3
	s_lshl_b32 s62, s62, 13
	s_add_i32 s62, s62, 0x10010
	v_add_u32_e32 v194, 0, v136
	v_xor_b32_e32 v194, v194, v137
	v_lshl_add_u32 v194, v194, 4, v133
	v_add_u32_e32 v160, s62, v194
	v_add_u32_e32 v194, s60, v194
	v_add_u32_e32 v195, 4, v136
	v_xor_b32_e32 v195, v195, v137
	v_lshl_add_u32 v195, v195, 4, v133
	v_add_u32_e32 v161, s62, v195
	v_add_u32_e32 v195, s60, v195
	v_lshrrev_b32_e32 v133, 3, v132
	s_mov_b32 s60, 0x1000
	v_mul_lo_u32 v133, v133, s60
	v_and_b32_e32 v136, 7, v132
	v_lshrrev_b32_e32 v137, 4, v132
	v_xor_b32_e32 v164, v137, v136
	v_lshl_add_u32 v164, v164, 4, v133
	v_add_u32_e32 v165, 4, v137
	v_xor_b32_e32 v165, v165, v136
	v_lshl_add_u32 v165, v165, 4, v133
	v_add_u32_e32 v165, 0x7c00, v165
	v_xor_b32_e32 v130, v137, v136
	v_lshl_add_u32 v130, v130, 4, v133
	v_add_u32_e32 v130, 0xf800, v130
	v_add_u32_e32 v131, 4, v137
	v_xor_b32_e32 v131, v131, v136
	v_lshl_add_u32 v131, v131, 4, v133
	v_add_u32_e32 v131, 0x17400, v131
	s_mul_i32 s60, s61, 0x20000
	s_add_u32 s52, s6, s60
	s_addc_u32 s53, s7, 0
	s_add_u32 s54, s8, s60
	s_addc_u32 s55, s9, 0
	s_lshl_b32 s58, s61, 12
	s_add_i32 s58, s58, 16
	s_add_i32 s59, s58, 0x10000
	s_mov_b32 s56, 0
	s_mov_b32 s57, 31
	s_barrier
	s_add_u32 m0, s58, 0x0
	s_nop 0
	global_load_lds_dwordx4 v164, s[52:53]
	global_load_lds_dwordx4 v165, s[52:53] offset:1024
	global_load_lds_dwordx4 v130, s[52:53] offset:2048
	global_load_lds_dwordx4 v131, s[52:53] offset:3072
	s_add_u32 m0, s59, 0x0
	s_nop 0
	global_load_lds_dwordx4 v164, s[54:55]
	global_load_lds_dwordx4 v165, s[54:55] offset:1024
	global_load_lds_dwordx4 v130, s[54:55] offset:2048
	global_load_lds_dwordx4 v131, s[54:55] offset:3072
	s_cmp_lt_u32 s56, s57
	s_cselect_b32 s60, 0x80, 0
	s_add_u32 s52, s52, s60
	s_addc_u32 s53, s53, 0
	s_add_u32 s54, s54, s60
	s_addc_u32 s55, s55, 0
	v_mov_b64_e32 v[114:115], 0
	v_mov_b64_e32 v[116:117], 0
	v_mov_b64_e32 v[118:119], 0
	v_mov_b64_e32 v[120:121], 0
	v_mov_b64_e32 v[122:123], 0
	v_mov_b64_e32 v[124:125], 0
	v_mov_b64_e32 v[126:127], 0
	v_mov_b64_e32 v[128:129], 0
	v_mov_b64_e32 v[98:99], 0
	v_mov_b64_e32 v[100:101], 0
	v_mov_b64_e32 v[102:103], 0
	v_mov_b64_e32 v[104:105], 0
	v_mov_b64_e32 v[106:107], 0
	v_mov_b64_e32 v[108:109], 0
	v_mov_b64_e32 v[110:111], 0
	v_mov_b64_e32 v[112:113], 0
	v_mov_b64_e32 v[82:83], 0
	v_mov_b64_e32 v[84:85], 0
	v_mov_b64_e32 v[86:87], 0
	v_mov_b64_e32 v[88:89], 0
	v_mov_b64_e32 v[90:91], 0
	v_mov_b64_e32 v[92:93], 0
	v_mov_b64_e32 v[94:95], 0
	v_mov_b64_e32 v[96:97], 0
	v_mov_b64_e32 v[66:67], 0
	v_mov_b64_e32 v[68:69], 0
	v_mov_b64_e32 v[70:71], 0
	v_mov_b64_e32 v[72:73], 0
	v_mov_b64_e32 v[74:75], 0
	v_mov_b64_e32 v[76:77], 0
	v_mov_b64_e32 v[78:79], 0
	v_mov_b64_e32 v[80:81], 0
	v_mov_b64_e32 v[50:51], 0
	v_mov_b64_e32 v[52:53], 0
	v_mov_b64_e32 v[54:55], 0
	v_mov_b64_e32 v[56:57], 0
	v_mov_b64_e32 v[58:59], 0
	v_mov_b64_e32 v[60:61], 0
	v_mov_b64_e32 v[62:63], 0
	v_mov_b64_e32 v[64:65], 0
	v_mov_b64_e32 v[34:35], 0
	v_mov_b64_e32 v[36:37], 0
	v_mov_b64_e32 v[38:39], 0
	v_mov_b64_e32 v[40:41], 0
	v_mov_b64_e32 v[42:43], 0
	v_mov_b64_e32 v[44:45], 0
	v_mov_b64_e32 v[46:47], 0
	v_mov_b64_e32 v[48:49], 0
	v_mov_b64_e32 v[18:19], 0
	v_mov_b64_e32 v[20:21], 0
	v_mov_b64_e32 v[22:23], 0
	v_mov_b64_e32 v[24:25], 0
	v_mov_b64_e32 v[26:27], 0
	v_mov_b64_e32 v[28:29], 0
	v_mov_b64_e32 v[30:31], 0
	v_mov_b64_e32 v[32:33], 0
	v_mov_b64_e32 v[2:3], 0
	v_mov_b64_e32 v[4:5], 0
	v_mov_b64_e32 v[6:7], 0
	v_mov_b64_e32 v[8:9], 0
	v_mov_b64_e32 v[10:11], 0
	v_mov_b64_e32 v[12:13], 0
	v_mov_b64_e32 v[14:15], 0
	v_mov_b64_e32 v[16:17], 0
	s_waitcnt vmcnt(0)
	s_barrier
	ds_read_b128 v[196:199], v194 offset:0
	ds_read_b128 v[212:215], v160 offset:0
	ds_read_b128 v[216:219], v160 offset:2048
	ds_read_b128 v[242:245], v160 offset:4096
	ds_read_b128 v[246:249], v160 offset:6144
	ds_read_b128 v[200:203], v194 offset:4096
	ds_read_b128 v[204:207], v194 offset:8192
	ds_read_b128 v[208:211], v194 offset:12288
	.p2alignl 6, 3212836864

; DI int tid512() { int t = threadIdx.x; asm volatile("" : "+v"(t)); return t; }
; DI unsigned voff256(size_t ld) { const int t = tid512(); return (unsigned)(((size_t)(t >> 3) * ld + (t & 7) * 8) * 2); }
; DI void gemm256(const char* a_u, unsigned a_voff, size_t astep, const char* b_u, unsigned b_voff, size_t bstep, int nk, char* smem, f32x16 (&acc)[4][2]) {
;   asm volatile("" : "+s"(nk));
;   const int t = tid512(), lane = t & 63, w = t >> 6, wm = w >> 2, wn = w & 3, r = lane & 31, h = lane >> 5;
;   const int soff = (t >> 3) * LROW + (t & 7) * 16;
;   const int aoff = (128 * wm + r) * LROW + h * 16, boff = T2 + (64 * wn + r) * LROW + h * 16;
;   u32x4 ra[4], rb[4];
; #pragma unroll
;   for (int i = 0; i < 4; ++i) { ra[i] = *(const u32x4*)(a_u + i * astep + a_voff); rb[i] = *(const u32x4*)(b_u + i * bstep + b_voff); }
;   __syncthreads();
; #pragma unroll
;   for (int i = 0; i < 4; ++i) { *(u32x4*)(smem + soff + i * 64 * LROW) = ra[i]; *(u32x4*)(smem + T2 + soff + i * 64 * LROW) = rb[i]; }
;   const int last = nk - 1;
;   {
;     const int k1 = last < 1 ? last : 1;
; #pragma unroll
;     for (int i = 0; i < 4; ++i) { ra[i] = *(const u32x4*)(a_u + i * astep + k1 * 128 + a_voff); rb[i] = *(const u32x4*)(b_u + i * bstep + k1 * 128 + b_voff); }
;   }
;   __syncthreads();
; DI void down256(const Params& p, int layer, char* smem) {
;     ...
;   for (int i = 0;; ++i) {
;     const int L = tile_of(i, 32 * 8);
;     if (L < 0) break;
;     int tm, tn; tile_mn(L, 32, 8, tm, tn);
;     f32x16 acc[4][2]; zero_acc256(acc);
;     gemm256((const char*)(HID + (size_t)(256 + tm * 256) * DFF), voff256(DFF), (size_t)128 * DFF, (const char*)(W + (size_t)(tn * 256) * DFF), voff256(DFF), (size_t)128 * DFF, DFF / 64, smem, acc);
.LBB0_1642:
	s_lshr_b32 s4, s6, 3
	s_and_b32 s4, s4, 0xffffffc
	s_sub_i32 s5, 32, s4
	s_min_i32 s5, s5, 4
	s_abs_i32 s11, s5
	v_cvt_f32_u32_e32 v2, s11
	s_sub_i32 s12, 0, s11
	s_and_b32 s7, s6, 31
	s_ashr_i32 s6, s5, 31
	v_rcp_iflag_f32_e32 v2, v2
	v_mov_b32_e32 v37, v181
	v_mul_f32_e32 v2, 0x4f7ffffe, v2
	v_cvt_u32_f32_e32 v2, v2
	s_nop 0
	v_readfirstlane_b32 s13, v2
	s_mul_i32 s12, s12, s13
	s_mul_hi_u32 s12, s13, s12
	s_add_i32 s13, s13, s12
	s_mul_hi_u32 s12, s7, s13
	s_mul_i32 s13, s12, s11
	s_sub_i32 s13, s7, s13
	s_add_i32 s14, s12, 1
	s_sub_i32 s15, s13, s11
	s_cmp_ge_u32 s13, s11
	s_cselect_b32 s12, s14, s12
	s_cselect_b32 s13, s15, s13
	s_add_i32 s14, s12, 1
	s_cmp_ge_u32 s13, s11
	s_cselect_b32 s11, s14, s12
	s_xor_b32 s11, s11, s6
	s_sub_i32 s6, s11, s6
	s_mul_i32 s5, s6, s5
	s_sub_i32 s5, s7, s5
	v_mov_b32_e32 v2, v0
	s_add_i32 s5, s5, s4
	s_lshl_b32 s11, s5, 8
	v_lshrrev_b32_e32 v3, 3, v2
	v_lshlrev_b32_e32 v2, 3, v2
	v_mul_lo_u32 v3, v3, s34
	s_addk_i32 s11, 0x100
	v_and_or_b32 v2, v2, 56, v3
	s_mul_i32 s4, s11, 0x2c00
	v_readlane_b32 s12, v254, 34
	v_lshlrev_b32_e32 v180, 1, v2
	v_mov_b32_e32 v2, v0
	s_mul_hi_u32 s5, s11, 0x2c00
	v_readlane_b32 s13, v254, 35
	s_add_u32 s4, s12, s4
	s_addc_u32 s5, s13, s5
	v_lshrrev_b32_e32 v3, 3, v2
	s_lshl_b32 s12, s6, 8
	s_mul_i32 s6, s6, 0x2c0000
	v_lshlrev_b32_e32 v2, 3, v2
	v_mul_lo_u32 v3, v3, s34
	s_mul_hi_i32 s7, s12, 0x2c00
	s_add_u32 s6, s8, s6
	v_and_or_b32 v2, v2, 56, v3
	v_lshl_add_u64 v[162:163], s[4:5], 0, v[180:181]
	s_addc_u32 s7, s9, s7
	v_lshlrev_b32_e32 v36, 1, v2
	v_add_co_u32_e32 v12, vcc, s26, v162
	v_lshl_add_u64 v[164:165], s[6:7], 0, v[36:37]
	s_nop 0
	v_addc_co_u32_e32 v13, vcc, 0, v163, vcc
	v_add_co_u32_e32 v16, vcc, s26, v164
	s_movk_i32 s13, 0x58
	v_mov_b32_e32 v2, v0
	v_addc_co_u32_e32 v17, vcc, 0, v165, vcc
	v_add_co_u32_e32 v20, vcc, s86, v162
	v_lshlrev_b32_e32 v4, 4, v2
	v_and_b32_e32 v38, 0x70, v4
	v_lshrrev_b32_e32 v132, 6, v0
	s_nop 0
	v_readfirstlane_b32 s61, v132
	v_and_b32_e32 v132, 63, v0
	v_and_b32_e32 v133, 15, v132
	v_lshrrev_b32_e32 v136, 4, v132
	v_bfe_u32 v137, v133, 1, 3
	v_lshlrev_b32_e32 v133, 7, v133
	s_lshr_b32 s60, s61, 2
	s_lshl_b32 s60, s60, 14
	s_add_i32 s60, s60, 16
	s_and_b32 s62, s61, 3
	s_lshl_b32 s62, s62, 13
	s_add_i32 s62, s62, 0x10010
	v_add_u32_e32 v194, 0, v136
	v_xor_b32_e32 v194, v194, v137
	v_lshl_add_u32 v194, v194, 4, v133
	v_add_u32_e32 v160, s62, v194
	v_add_u32_e32 v194, s60, v194
	v_add_u32_e32 v195, 4, v136
	v_xor_b32_e32 v195, v195, v137
	v_lshl_add_u32 v195, v195, 4, v133
	v_add_u32_e32 v161, s62, v195
	v_add_u32_e32 v195, s60, v195
	v_lshrrev_b32_e32 v133, 3, v132
	s_mov_b32 s60, 0x2c00
	v_mul_lo_u32 v133, v133, s60
	v_and_b32_e32 v136, 7, v132
	v_lshrrev_b32_e32 v137, 4, v132
	v_xor_b32_e32 v164, v137, v136
	v_lshl_add_u32 v164, v164, 4, v133
	v_add_u32_e32 v165, 4, v137
	v_xor_b32_e32 v165, v165, v136
	v_lshl_add_u32 v165, v165, 4, v133
	v_add_u32_e32 v165, 0x15c00, v165
	v_xor_b32_e32 v130, v137, v136
	v_lshl_add_u32 v130, v130, 4, v133
	v_add_u32_e32 v130, 0x2b800, v130
	v_add_u32_e32 v131, 4, v137
	v_xor_b32_e32 v131, v131, v136
	v_lshl_add_u32 v131, v131, 4, v133
	v_add_u32_e32 v131, 0x41400, v131
	s_mul_i32 s60, s61, 0x58000
	s_add_u32 s52, s4, s60
	s_addc_u32 s53, s5, 0
	s_add_u32 s54, s6, s60
	s_addc_u32 s55, s7, 0
	s_lshl_b32 s58, s61, 12
	s_add_i32 s58, s58, 16
	s_add_i32 s59, s58, 0x10000
	s_mov_b32 s56, 0
	s_mov_b32 s57, 87
	s_barrier
	s_add_u32 m0, s58, 0x0
	s_nop 0
	global_load_lds_dwordx4 v164, s[52:53]
	global_load_lds_dwordx4 v165, s[52:53] offset:1024
	global_load_lds_dwordx4 v130, s[52:53] offset:2048
	global_load_lds_dwordx4 v131, s[52:53] offset:3072
	s_add_u32 m0, s59, 0x0
	s_nop 0
	global_load_lds_dwordx4 v164, s[54:55]
	global_load_lds_dwordx4 v165, s[54:55] offset:1024
	global_load_lds_dwordx4 v130, s[54:55] offset:2048
	global_load_lds_dwordx4 v131, s[54:55] offset:3072
	s_cmp_lt_u32 s56, s57
	s_cselect_b32 s60, 0x80, 0
	s_add_u32 s52, s52, s60
	s_addc_u32 s53, s53, 0
	s_add_u32 s54, s54, s60
	s_addc_u32 s55, s55, 0
	v_mov_b64_e32 v[114:115], 0
	v_mov_b64_e32 v[116:117], 0
	v_mov_b64_e32 v[118:119], 0
	v_mov_b64_e32 v[120:121], 0
	v_mov_b64_e32 v[122:123], 0
	v_mov_b64_e32 v[124:125], 0
	v_mov_b64_e32 v[126:127], 0
	v_mov_b64_e32 v[128:129], 0
	v_mov_b64_e32 v[98:99], 0
	v_mov_b64_e32 v[100:101], 0
	v_mov_b64_e32 v[102:103], 0
	v_mov_b64_e32 v[104:105], 0
	v_mov_b64_e32 v[106:107], 0
	v_mov_b64_e32 v[108:109], 0
	v_mov_b64_e32 v[110:111], 0
	v_mov_b64_e32 v[112:113], 0
	v_mov_b64_e32 v[82:83], 0
	v_mov_b64_e32 v[84:85], 0
	v_mov_b64_e32 v[86:87], 0
	v_mov_b64_e32 v[88:89], 0
	v_mov_b64_e32 v[90:91], 0
	v_mov_b64_e32 v[92:93], 0
	v_mov_b64_e32 v[94:95], 0
	v_mov_b64_e32 v[96:97], 0
	v_mov_b64_e32 v[66:67], 0
	v_mov_b64_e32 v[68:69], 0
	v_mov_b64_e32 v[70:71], 0
	v_mov_b64_e32 v[72:73], 0
	v_mov_b64_e32 v[74:75], 0
	v_mov_b64_e32 v[76:77], 0
	v_mov_b64_e32 v[78:79], 0
	v_mov_b64_e32 v[80:81], 0
	v_mov_b64_e32 v[50:51], 0
	v_mov_b64_e32 v[52:53], 0
	v_mov_b64_e32 v[54:55], 0
	v_mov_b64_e32 v[56:57], 0
	v_mov_b64_e32 v[58:59], 0
	v_mov_b64_e32 v[60:61], 0
	v_mov_b64_e32 v[62:63], 0
	v_mov_b64_e32 v[64:65], 0
	v_mov_b64_e32 v[34:35], 0
	v_mov_b64_e32 v[36:37], 0
	v_mov_b64_e32 v[38:39], 0
	v_mov_b64_e32 v[40:41], 0
	v_mov_b64_e32 v[42:43], 0
	v_mov_b64_e32 v[44:45], 0
	v_mov_b64_e32 v[46:47], 0
	v_mov_b64_e32 v[48:49], 0
	v_mov_b64_e32 v[18:19], 0
	v_mov_b64_e32 v[20:21], 0
	v_mov_b64_e32 v[22:23], 0
	v_mov_b64_e32 v[24:25], 0
	v_mov_b64_e32 v[26:27], 0
	v_mov_b64_e32 v[28:29], 0
	v_mov_b64_e32 v[30:31], 0
	v_mov_b64_e32 v[32:33], 0
	v_mov_b64_e32 v[2:3], 0
	v_mov_b64_e32 v[4:5], 0
	v_mov_b64_e32 v[6:7], 0
	v_mov_b64_e32 v[8:9], 0
	v_mov_b64_e32 v[10:11], 0
	v_mov_b64_e32 v[12:13], 0
	v_mov_b64_e32 v[14:15], 0
	v_mov_b64_e32 v[16:17], 0
	s_waitcnt vmcnt(0)
	s_barrier
	ds_read_b128 v[196:199], v194 offset:0
	ds_read_b128 v[212:215], v160 offset:0
	ds_read_b128 v[216:219], v160 offset:2048
	ds_read_b128 v[242:245], v160 offset:4096
	ds_read_b128 v[246:249], v160 offset:6144
	ds_read_b128 v[200:203], v194 offset:4096
	ds_read_b128 v[204:207], v194 offset:8192
	ds_read_b128 v[208:211], v194 offset:12288
	.p2alignl 6, 3212836864
